# grid barrier: top-level last arriver bumps all XCD release generations directly (leaders no longer re-broadcast), on top of early acquire invalidate
# speedup vs baseline: 1.0052x; 1.0001x over previous
; __device__ __forceinline__ unsigned xb_ld(unsigned* p)              { return __hip_atomic_load(p, __ATOMIC_RELAXED, __HIP_MEMORY_SCOPE_AGENT); }
; __device__ __forceinline__ unsigned xb_add(unsigned* p, unsigned v) { return __hip_atomic_fetch_add(p, v, __ATOMIC_RELAXED, __HIP_MEMORY_SCOPE_AGENT); }
; #define XB_SPIN(cond, bar) do { unsigned _sp = 0; while (cond) { __builtin_amdgcn_s_sleep(1); \
;     if ((++_sp & 255u) == 0u) { if (xb_ld(&(bar)[XB_TMO])) break; if (_sp > XB_SPIN_CAP) { atomicAdd(&(bar)[XB_TMO], 1u); break; } } } } while (0)
; __device__ __forceinline__ void xcd_barrier(unsigned* bar, volatile LAS unsigned* st, bool tid0) {
;     ...
;             const unsigned og = xb_add(&bar[XB_TOP], 1u);
;             const unsigned tg = og / nx;
;             if (og + 1u == (tg + 1u) * nx) xb_add(&bar[XB_TOPGEN], 1u);
;             else XB_SPIN(xb_ld(&bar[XB_TOPGEN]) == tg, bar);
.LBB0_64:
	s_or_b64 exec, exec, s[8:9]
	v_cvt_f32_u32_e32 v4, v1
	s_waitcnt vmcnt(0)
	v_readfirstlane_b32 s2, v3
	s_add_u32 s8, s52, 0x3500
	s_addc_u32 s9, s53, 0
	v_rcp_iflag_f32_e32 v4, v4
	v_add_u32_e32 v2, s2, v2
	v_add_u32_e32 v5, 1, v2
	s_mov_b64 s[10:11], -1
	v_mul_f32_e32 v3, 0x4f7ffffe, v4
	v_cvt_u32_f32_e32 v3, v3
	v_sub_u32_e32 v4, 0, v1
	v_mul_lo_u32 v4, v4, v3
	v_mul_hi_u32 v4, v3, v4
	v_add_u32_e32 v3, v3, v4
	v_mul_hi_u32 v3, v2, v3
	v_mul_lo_u32 v4, v3, v1
	v_sub_u32_e32 v2, v2, v4
	v_add_u32_e32 v6, 1, v3
	v_cmp_ge_u32_e32 vcc, v2, v1
	v_sub_u32_e32 v4, v2, v1
	s_nop 0
	v_cndmask_b32_e32 v3, v3, v6, vcc
	v_cndmask_b32_e32 v2, v2, v4, vcc
	v_add_u32_e32 v4, 1, v3
	v_cmp_ge_u32_e32 vcc, v2, v1
	s_nop 1
	v_cndmask_b32_e32 v4, v3, v4, vcc
	v_mul_lo_u32 v2, v1, v4
	v_add_u32_e32 v1, v2, v1
	v_cmp_ne_u32_e32 vcc, v5, v1
	v_mov_b64_e32 v[2:3], s[8:9]
	s_cbranch_vccnz .Lxb_bcast_skip_0
	v_mov_b32_e32 v5, 0x2400
	v_mov_b32_e32 v6, 1
	global_atomic_add v5, v6, s[52:53]
	global_atomic_add v5, v6, s[52:53] offset:256
	global_atomic_add v5, v6, s[52:53] offset:512
	global_atomic_add v5, v6, s[52:53] offset:768
	global_atomic_add v5, v6, s[52:53] offset:1024
	global_atomic_add v5, v6, s[52:53] offset:1280
	global_atomic_add v5, v6, s[52:53] offset:1536
	global_atomic_add v5, v6, s[52:53] offset:1792
	global_atomic_add v5, v6, s[52:53] offset:2048
	global_atomic_add v5, v6, s[52:53] offset:2304
	global_atomic_add v5, v6, s[52:53] offset:2560
	global_atomic_add v5, v6, s[52:53] offset:2816
	global_atomic_add v5, v6, s[52:53] offset:3072
	global_atomic_add v5, v6, s[52:53] offset:3328
	global_atomic_add v5, v6, s[52:53] offset:3584
	global_atomic_add v5, v6, s[52:53] offset:3840
.Lxb_bcast_skip_0:
	s_and_saveexec_b64 s[6:7], vcc
	s_cbranch_execz .LBB0_76
	v_mov_b32_e32 v1, 0
	global_load_dword v2, v1, s[8:9] sc1
	s_mov_b64 s[14:15], 0
	s_waitcnt vmcnt(0)
	v_cmp_eq_u32_e32 vcc, v2, v4
	s_and_saveexec_b64 s[12:13], vcc
	s_cbranch_execz .LBB0_75
	s_add_u32 s10, s52, 0x200
	s_addc_u32 s11, s53, 0
	s_mov_b32 s2, 1
	s_branch .LBB0_68

; __device__ __forceinline__ unsigned xb_add(unsigned* p, unsigned v) { return __hip_atomic_fetch_add(p, v, __ATOMIC_RELAXED, __HIP_MEMORY_SCOPE_AGENT); }
; __device__ __forceinline__ void xcd_barrier(unsigned* bar, volatile LAS unsigned* st, bool tid0) {
;     ...
;             __builtin_amdgcn_fence(__ATOMIC_ACQUIRE, "agent");
;             xb_add(&bar[XB_XGEN(x)], 1u);
;             asm volatile("s_waitcnt vmcnt(0)" ::: "memory");
.LBB0_78:
	s_or_b64 exec, exec, s[6:7]
	s_mov_b64 s[6:7], exec
	v_mbcnt_lo_u32_b32 v1, s6, 0
	v_mbcnt_hi_u32_b32 v1, s7, v1
	v_cmp_eq_u32_e32 vcc, 0, v1
	s_waitcnt vmcnt(0)
	s_and_saveexec_b64 s[8:9], vcc
	s_cbranch_execz .LBB0_80
	s_bcnt1_i32_b64 s2, s[6:7]
	v_mov_b32_e32 v1, 0x2000
	v_mov_b32_e32 v2, s2
.LBB0_80:
	s_or_b64 exec, exec, s[8:9]
	s_waitcnt vmcnt(0)

; __device__ __forceinline__ unsigned xb_ld(unsigned* p)              { return __hip_atomic_load(p, __ATOMIC_RELAXED, __HIP_MEMORY_SCOPE_AGENT); }
; __device__ __forceinline__ unsigned xb_add(unsigned* p, unsigned v) { return __hip_atomic_fetch_add(p, v, __ATOMIC_RELAXED, __HIP_MEMORY_SCOPE_AGENT); }
; #define XB_SPIN(cond, bar) do { unsigned _sp = 0; while (cond) { __builtin_amdgcn_s_sleep(1); \
;     if ((++_sp & 255u) == 0u) { if (xb_ld(&(bar)[XB_TMO])) break; if (_sp > XB_SPIN_CAP) { atomicAdd(&(bar)[XB_TMO], 1u); break; } } } } while (0)
; __device__ __forceinline__ void xcd_barrier(unsigned* bar, volatile LAS unsigned* st, bool tid0) {
;     ...
;             const unsigned og = xb_add(&bar[XB_TOP], 1u);
;             const unsigned tg = og / nx;
;             if (og + 1u == (tg + 1u) * nx) xb_add(&bar[XB_TOPGEN], 1u);
;             else XB_SPIN(xb_ld(&bar[XB_TOPGEN]) == tg, bar);
.LBB0_206:
	s_or_b64 exec, exec, s[10:11]
	v_cvt_f32_u32_e32 v3, v0
	s_waitcnt vmcnt(0)
	v_readfirstlane_b32 s2, v2
	s_add_u32 s10, s52, 0x3500
	s_addc_u32 s11, s53, 0
	v_rcp_iflag_f32_e32 v3, v3
	v_add_u32_e32 v1, s2, v1
	v_add_u32_e32 v4, 1, v1
	s_mov_b64 s[12:13], -1
	v_mul_f32_e32 v2, 0x4f7ffffe, v3
	v_cvt_u32_f32_e32 v2, v2
	v_sub_u32_e32 v3, 0, v0
	v_mul_lo_u32 v3, v3, v2
	v_mul_hi_u32 v3, v2, v3
	v_add_u32_e32 v2, v2, v3
	v_mul_hi_u32 v2, v1, v2
	v_mul_lo_u32 v3, v2, v0
	v_sub_u32_e32 v1, v1, v3
	v_add_u32_e32 v5, 1, v2
	v_cmp_ge_u32_e32 vcc, v1, v0
	v_sub_u32_e32 v3, v1, v0
	s_nop 0
	v_cndmask_b32_e32 v2, v2, v5, vcc
	v_cndmask_b32_e32 v1, v1, v3, vcc
	v_add_u32_e32 v3, 1, v2
	v_cmp_ge_u32_e32 vcc, v1, v0
	s_nop 1
	v_cndmask_b32_e32 v2, v2, v3, vcc
	v_mul_lo_u32 v1, v0, v2
	v_add_u32_e32 v0, v1, v0
	v_cmp_ne_u32_e32 vcc, v4, v0
	v_mov_b64_e32 v[0:1], s[10:11]
	s_cbranch_vccnz .Lxb_bcast_skip_1
	v_mov_b32_e32 v3, 0x2400
	v_mov_b32_e32 v4, 1
	global_atomic_add v3, v4, s[52:53]
	global_atomic_add v3, v4, s[52:53] offset:256
	global_atomic_add v3, v4, s[52:53] offset:512
	global_atomic_add v3, v4, s[52:53] offset:768
	global_atomic_add v3, v4, s[52:53] offset:1024
	global_atomic_add v3, v4, s[52:53] offset:1280
	global_atomic_add v3, v4, s[52:53] offset:1536
	global_atomic_add v3, v4, s[52:53] offset:1792
	global_atomic_add v3, v4, s[52:53] offset:2048
	global_atomic_add v3, v4, s[52:53] offset:2304
	global_atomic_add v3, v4, s[52:53] offset:2560
	global_atomic_add v3, v4, s[52:53] offset:2816
	global_atomic_add v3, v4, s[52:53] offset:3072
	global_atomic_add v3, v4, s[52:53] offset:3328
	global_atomic_add v3, v4, s[52:53] offset:3584
	global_atomic_add v3, v4, s[52:53] offset:3840
.Lxb_bcast_skip_1:
	s_and_saveexec_b64 s[8:9], vcc
	s_cbranch_execz .LBB0_218
	v_mov_b32_e32 v0, 0
	global_load_dword v1, v0, s[10:11] sc1
	s_mov_b64 s[16:17], 0
	s_waitcnt vmcnt(0)
	v_cmp_eq_u32_e32 vcc, v1, v2
	s_and_saveexec_b64 s[14:15], vcc
	s_cbranch_execz .LBB0_217
	s_add_u32 s12, s52, 0x200
	s_addc_u32 s13, s53, 0
	s_mov_b32 s2, 1
	s_branch .LBB0_210

; __device__ __forceinline__ unsigned xb_add(unsigned* p, unsigned v) { return __hip_atomic_fetch_add(p, v, __ATOMIC_RELAXED, __HIP_MEMORY_SCOPE_AGENT); }
; __device__ __forceinline__ void xcd_barrier(unsigned* bar, volatile LAS unsigned* st, bool tid0) {
;     ...
;             __builtin_amdgcn_fence(__ATOMIC_ACQUIRE, "agent");
;             xb_add(&bar[XB_XGEN(x)], 1u);
;             asm volatile("s_waitcnt vmcnt(0)" ::: "memory");
.LBB0_220:
	s_or_b64 exec, exec, s[8:9]
	s_mov_b64 s[8:9], exec
	v_mbcnt_lo_u32_b32 v0, s8, 0
	v_mbcnt_hi_u32_b32 v0, s9, v0
	v_cmp_eq_u32_e32 vcc, 0, v0
	s_waitcnt vmcnt(0)
	s_and_saveexec_b64 s[10:11], vcc
	s_cbranch_execz .LBB0_222
	s_bcnt1_i32_b64 s2, s[8:9]
	v_mov_b32_e32 v0, 0x2000
	v_mov_b32_e32 v1, s2
.LBB0_222:
	s_or_b64 exec, exec, s[10:11]
	s_waitcnt vmcnt(0)

; __device__ __forceinline__ unsigned xb_ld(unsigned* p)              { return __hip_atomic_load(p, __ATOMIC_RELAXED, __HIP_MEMORY_SCOPE_AGENT); }
; __device__ __forceinline__ unsigned xb_add(unsigned* p, unsigned v) { return __hip_atomic_fetch_add(p, v, __ATOMIC_RELAXED, __HIP_MEMORY_SCOPE_AGENT); }
; #define XB_SPIN(cond, bar) do { unsigned _sp = 0; while (cond) { __builtin_amdgcn_s_sleep(1); \
;     if ((++_sp & 255u) == 0u) { if (xb_ld(&(bar)[XB_TMO])) break; if (_sp > XB_SPIN_CAP) { atomicAdd(&(bar)[XB_TMO], 1u); break; } } } } while (0)
; __device__ __forceinline__ void xcd_barrier(unsigned* bar, volatile LAS unsigned* st, bool tid0) {
;     ...
;             const unsigned og = xb_add(&bar[XB_TOP], 1u);
;             const unsigned tg = og / nx;
;             if (og + 1u == (tg + 1u) * nx) xb_add(&bar[XB_TOPGEN], 1u);
;             else XB_SPIN(xb_ld(&bar[XB_TOPGEN]) == tg, bar);
.LBB0_270:
	s_or_b64 exec, exec, s[10:11]
	v_cvt_f32_u32_e32 v3, v0
	s_waitcnt vmcnt(0)
	v_readfirstlane_b32 s3, v2
	s_add_u32 s10, s52, 0x3500
	s_addc_u32 s11, s53, 0
	v_rcp_iflag_f32_e32 v3, v3
	v_add_u32_e32 v1, s3, v1
	v_add_u32_e32 v4, 1, v1
	s_mov_b64 s[16:17], -1
	v_mul_f32_e32 v2, 0x4f7ffffe, v3
	v_cvt_u32_f32_e32 v2, v2
	v_sub_u32_e32 v3, 0, v0
	v_mul_lo_u32 v3, v3, v2
	v_mul_hi_u32 v3, v2, v3
	v_add_u32_e32 v2, v2, v3
	v_mul_hi_u32 v2, v1, v2
	v_mul_lo_u32 v3, v2, v0
	v_sub_u32_e32 v1, v1, v3
	v_add_u32_e32 v5, 1, v2
	v_cmp_ge_u32_e32 vcc, v1, v0
	v_sub_u32_e32 v3, v1, v0
	s_nop 0
	v_cndmask_b32_e32 v2, v2, v5, vcc
	v_cndmask_b32_e32 v1, v1, v3, vcc
	v_add_u32_e32 v3, 1, v2
	v_cmp_ge_u32_e32 vcc, v1, v0
	s_nop 1
	v_cndmask_b32_e32 v2, v2, v3, vcc
	v_mul_lo_u32 v1, v0, v2
	v_add_u32_e32 v0, v1, v0
	v_cmp_ne_u32_e32 vcc, v4, v0
	v_mov_b64_e32 v[0:1], s[10:11]
	s_cbranch_vccnz .Lxb_bcast_skip_2
	v_mov_b32_e32 v3, 0x2400
	v_mov_b32_e32 v4, 1
	global_atomic_add v3, v4, s[52:53]
	global_atomic_add v3, v4, s[52:53] offset:256
	global_atomic_add v3, v4, s[52:53] offset:512
	global_atomic_add v3, v4, s[52:53] offset:768
	global_atomic_add v3, v4, s[52:53] offset:1024
	global_atomic_add v3, v4, s[52:53] offset:1280
	global_atomic_add v3, v4, s[52:53] offset:1536
	global_atomic_add v3, v4, s[52:53] offset:1792
	global_atomic_add v3, v4, s[52:53] offset:2048
	global_atomic_add v3, v4, s[52:53] offset:2304
	global_atomic_add v3, v4, s[52:53] offset:2560
	global_atomic_add v3, v4, s[52:53] offset:2816
	global_atomic_add v3, v4, s[52:53] offset:3072
	global_atomic_add v3, v4, s[52:53] offset:3328
	global_atomic_add v3, v4, s[52:53] offset:3584
	global_atomic_add v3, v4, s[52:53] offset:3840
.Lxb_bcast_skip_2:
	s_and_saveexec_b64 s[8:9], vcc
	s_cbranch_execz .LBB0_282
	v_mov_b32_e32 v0, 0
	global_load_dword v1, v0, s[10:11] sc1
	s_mov_b64 s[20:21], 0
	s_waitcnt vmcnt(0)
	v_cmp_eq_u32_e32 vcc, v1, v2
	s_and_saveexec_b64 s[18:19], vcc
	s_cbranch_execz .LBB0_281
	s_add_u32 s16, s52, 0x200
	s_addc_u32 s17, s53, 0
	s_mov_b32 s3, 1
	s_branch .LBB0_274

; __device__ __forceinline__ unsigned xb_add(unsigned* p, unsigned v) { return __hip_atomic_fetch_add(p, v, __ATOMIC_RELAXED, __HIP_MEMORY_SCOPE_AGENT); }
; __device__ __forceinline__ void xcd_barrier(unsigned* bar, volatile LAS unsigned* st, bool tid0) {
;     ...
;             __builtin_amdgcn_fence(__ATOMIC_ACQUIRE, "agent");
;             xb_add(&bar[XB_XGEN(x)], 1u);
;             asm volatile("s_waitcnt vmcnt(0)" ::: "memory");
.LBB0_284:
	s_or_b64 exec, exec, s[8:9]
	s_mov_b64 s[8:9], exec
	v_mbcnt_lo_u32_b32 v0, s8, 0
	v_mbcnt_hi_u32_b32 v0, s9, v0
	v_cmp_eq_u32_e32 vcc, 0, v0
	s_waitcnt vmcnt(0)
	s_and_saveexec_b64 s[10:11], vcc
	s_cbranch_execz .LBB0_286
	s_bcnt1_i32_b64 s3, s[8:9]
	v_mov_b32_e32 v0, 0x2000
	v_mov_b32_e32 v1, s3
.LBB0_286:
	s_or_b64 exec, exec, s[10:11]
	s_waitcnt vmcnt(0)

; __device__ __forceinline__ unsigned xb_ld(unsigned* p)              { return __hip_atomic_load(p, __ATOMIC_RELAXED, __HIP_MEMORY_SCOPE_AGENT); }
; __device__ __forceinline__ unsigned xb_add(unsigned* p, unsigned v) { return __hip_atomic_fetch_add(p, v, __ATOMIC_RELAXED, __HIP_MEMORY_SCOPE_AGENT); }
; #define XB_SPIN(cond, bar) do { unsigned _sp = 0; while (cond) { __builtin_amdgcn_s_sleep(1); \
;     if ((++_sp & 255u) == 0u) { if (xb_ld(&(bar)[XB_TMO])) break; if (_sp > XB_SPIN_CAP) { atomicAdd(&(bar)[XB_TMO], 1u); break; } } } } while (0)
; __device__ __forceinline__ void xcd_barrier(unsigned* bar, volatile LAS unsigned* st, bool tid0) {
;     ...
;             const unsigned og = xb_add(&bar[XB_TOP], 1u);
;             const unsigned tg = og / nx;
;             if (og + 1u == (tg + 1u) * nx) xb_add(&bar[XB_TOPGEN], 1u);
;             else XB_SPIN(xb_ld(&bar[XB_TOPGEN]) == tg, bar);
.LBB0_328:
	s_or_b64 exec, exec, s[8:9]
	v_cvt_f32_u32_e32 v3, v0
	s_waitcnt vmcnt(0)
	v_readfirstlane_b32 s3, v2
	s_add_u32 s8, s52, 0x3500
	s_addc_u32 s9, s53, 0
	v_rcp_iflag_f32_e32 v3, v3
	v_add_u32_e32 v1, s3, v1
	v_add_u32_e32 v4, 1, v1
	s_mov_b64 s[10:11], -1
	v_mul_f32_e32 v2, 0x4f7ffffe, v3
	v_cvt_u32_f32_e32 v2, v2
	v_sub_u32_e32 v3, 0, v0
	v_mul_lo_u32 v3, v3, v2
	v_mul_hi_u32 v3, v2, v3
	v_add_u32_e32 v2, v2, v3
	v_mul_hi_u32 v2, v1, v2
	v_mul_lo_u32 v3, v2, v0
	v_sub_u32_e32 v1, v1, v3
	v_add_u32_e32 v5, 1, v2
	v_cmp_ge_u32_e32 vcc, v1, v0
	v_sub_u32_e32 v3, v1, v0
	s_nop 0
	v_cndmask_b32_e32 v2, v2, v5, vcc
	v_cndmask_b32_e32 v1, v1, v3, vcc
	v_add_u32_e32 v3, 1, v2
	v_cmp_ge_u32_e32 vcc, v1, v0
	s_nop 1
	v_cndmask_b32_e32 v2, v2, v3, vcc
	v_mul_lo_u32 v1, v0, v2
	v_add_u32_e32 v0, v1, v0
	v_cmp_ne_u32_e32 vcc, v4, v0
	v_mov_b64_e32 v[0:1], s[8:9]
	s_cbranch_vccnz .Lxb_bcast_skip_3
	v_mov_b32_e32 v3, 0x2400
	v_mov_b32_e32 v4, 1
	global_atomic_add v3, v4, s[52:53]
	global_atomic_add v3, v4, s[52:53] offset:256
	global_atomic_add v3, v4, s[52:53] offset:512
	global_atomic_add v3, v4, s[52:53] offset:768
	global_atomic_add v3, v4, s[52:53] offset:1024
	global_atomic_add v3, v4, s[52:53] offset:1280
	global_atomic_add v3, v4, s[52:53] offset:1536
	global_atomic_add v3, v4, s[52:53] offset:1792
	global_atomic_add v3, v4, s[52:53] offset:2048
	global_atomic_add v3, v4, s[52:53] offset:2304
	global_atomic_add v3, v4, s[52:53] offset:2560
	global_atomic_add v3, v4, s[52:53] offset:2816
	global_atomic_add v3, v4, s[52:53] offset:3072
	global_atomic_add v3, v4, s[52:53] offset:3328
	global_atomic_add v3, v4, s[52:53] offset:3584
	global_atomic_add v3, v4, s[52:53] offset:3840
.Lxb_bcast_skip_3:
	s_and_saveexec_b64 s[6:7], vcc
	s_cbranch_execz .LBB0_340
	v_mov_b32_e32 v0, 0
	global_load_dword v1, v0, s[8:9] sc1
	s_mov_b64 s[18:19], 0
	s_waitcnt vmcnt(0)
	v_cmp_eq_u32_e32 vcc, v1, v2
	s_and_saveexec_b64 s[16:17], vcc
	s_cbranch_execz .LBB0_339
	s_add_u32 s10, s52, 0x200
	s_addc_u32 s11, s53, 0
	s_mov_b32 s3, 1
	s_branch .LBB0_332

; __device__ __forceinline__ unsigned xb_add(unsigned* p, unsigned v) { return __hip_atomic_fetch_add(p, v, __ATOMIC_RELAXED, __HIP_MEMORY_SCOPE_AGENT); }
; __device__ __forceinline__ void xcd_barrier(unsigned* bar, volatile LAS unsigned* st, bool tid0) {
;     ...
;             __builtin_amdgcn_fence(__ATOMIC_ACQUIRE, "agent");
;             xb_add(&bar[XB_XGEN(x)], 1u);
;             asm volatile("s_waitcnt vmcnt(0)" ::: "memory");
.LBB0_342:
	s_or_b64 exec, exec, s[6:7]
	s_mov_b64 s[6:7], exec
	v_mbcnt_lo_u32_b32 v0, s6, 0
	v_mbcnt_hi_u32_b32 v0, s7, v0
	v_cmp_eq_u32_e32 vcc, 0, v0
	s_waitcnt vmcnt(0)
	s_and_saveexec_b64 s[8:9], vcc
	s_cbranch_execz .LBB0_344
	s_bcnt1_i32_b64 s3, s[6:7]
	v_mov_b32_e32 v0, 0x2000
	v_mov_b32_e32 v1, s3
.LBB0_344:
	s_or_b64 exec, exec, s[8:9]
	s_waitcnt vmcnt(0)

; __device__ __forceinline__ unsigned xb_ld(unsigned* p)              { return __hip_atomic_load(p, __ATOMIC_RELAXED, __HIP_MEMORY_SCOPE_AGENT); }
; __device__ __forceinline__ unsigned xb_add(unsigned* p, unsigned v) { return __hip_atomic_fetch_add(p, v, __ATOMIC_RELAXED, __HIP_MEMORY_SCOPE_AGENT); }
; #define XB_SPIN(cond, bar) do { unsigned _sp = 0; while (cond) { __builtin_amdgcn_s_sleep(1); \
;     if ((++_sp & 255u) == 0u) { if (xb_ld(&(bar)[XB_TMO])) break; if (_sp > XB_SPIN_CAP) { atomicAdd(&(bar)[XB_TMO], 1u); break; } } } } while (0)
; __device__ __forceinline__ void xcd_barrier(unsigned* bar, volatile LAS unsigned* st, bool tid0) {
;     ...
;             const unsigned og = xb_add(&bar[XB_TOP], 1u);
;             const unsigned tg = og / nx;
;             if (og + 1u == (tg + 1u) * nx) xb_add(&bar[XB_TOPGEN], 1u);
;             else XB_SPIN(xb_ld(&bar[XB_TOPGEN]) == tg, bar);
.LBB0_479:
	s_or_b64 exec, exec, s[8:9]
	v_cvt_f32_u32_e32 v3, v0
	s_waitcnt vmcnt(0)
	v_readfirstlane_b32 s2, v2
	s_add_u32 s8, s52, 0x3500
	s_addc_u32 s9, s53, 0
	v_rcp_iflag_f32_e32 v3, v3
	v_add_u32_e32 v1, s2, v1
	v_add_u32_e32 v4, 1, v1
	s_mov_b64 s[10:11], -1
	v_mul_f32_e32 v2, 0x4f7ffffe, v3
	v_cvt_u32_f32_e32 v2, v2
	v_sub_u32_e32 v3, 0, v0
	v_mul_lo_u32 v3, v3, v2
	v_mul_hi_u32 v3, v2, v3
	v_add_u32_e32 v2, v2, v3
	v_mul_hi_u32 v2, v1, v2
	v_mul_lo_u32 v3, v2, v0
	v_sub_u32_e32 v1, v1, v3
	v_add_u32_e32 v5, 1, v2
	v_cmp_ge_u32_e32 vcc, v1, v0
	v_sub_u32_e32 v3, v1, v0
	s_nop 0
	v_cndmask_b32_e32 v2, v2, v5, vcc
	v_cndmask_b32_e32 v1, v1, v3, vcc
	v_add_u32_e32 v3, 1, v2
	v_cmp_ge_u32_e32 vcc, v1, v0
	s_nop 1
	v_cndmask_b32_e32 v2, v2, v3, vcc
	v_mul_lo_u32 v1, v0, v2
	v_add_u32_e32 v0, v1, v0
	v_cmp_ne_u32_e32 vcc, v4, v0
	v_mov_b64_e32 v[0:1], s[8:9]
	s_cbranch_vccnz .Lxb_bcast_skip_4
	v_mov_b32_e32 v3, 0x2400
	v_mov_b32_e32 v4, 1
	global_atomic_add v3, v4, s[52:53]
	global_atomic_add v3, v4, s[52:53] offset:256
	global_atomic_add v3, v4, s[52:53] offset:512
	global_atomic_add v3, v4, s[52:53] offset:768
	global_atomic_add v3, v4, s[52:53] offset:1024
	global_atomic_add v3, v4, s[52:53] offset:1280
	global_atomic_add v3, v4, s[52:53] offset:1536
	global_atomic_add v3, v4, s[52:53] offset:1792
	global_atomic_add v3, v4, s[52:53] offset:2048
	global_atomic_add v3, v4, s[52:53] offset:2304
	global_atomic_add v3, v4, s[52:53] offset:2560
	global_atomic_add v3, v4, s[52:53] offset:2816
	global_atomic_add v3, v4, s[52:53] offset:3072
	global_atomic_add v3, v4, s[52:53] offset:3328
	global_atomic_add v3, v4, s[52:53] offset:3584
	global_atomic_add v3, v4, s[52:53] offset:3840
.Lxb_bcast_skip_4:
	s_and_saveexec_b64 s[6:7], vcc
	s_cbranch_execz .LBB0_491
	v_mov_b32_e32 v0, 0
	global_load_dword v1, v0, s[8:9] sc1
	s_mov_b64 s[14:15], 0
	s_waitcnt vmcnt(0)
	v_cmp_eq_u32_e32 vcc, v1, v2
	s_and_saveexec_b64 s[12:13], vcc
	s_cbranch_execz .LBB0_490
	s_add_u32 s10, s52, 0x200
	s_addc_u32 s11, s53, 0
	s_mov_b32 s2, 1
	s_branch .LBB0_483

; __device__ __forceinline__ unsigned xb_add(unsigned* p, unsigned v) { return __hip_atomic_fetch_add(p, v, __ATOMIC_RELAXED, __HIP_MEMORY_SCOPE_AGENT); }
; __device__ __forceinline__ void xcd_barrier(unsigned* bar, volatile LAS unsigned* st, bool tid0) {
;     ...
;             __builtin_amdgcn_fence(__ATOMIC_ACQUIRE, "agent");
;             xb_add(&bar[XB_XGEN(x)], 1u);
;             asm volatile("s_waitcnt vmcnt(0)" ::: "memory");
.LBB0_493:
	s_or_b64 exec, exec, s[6:7]
	s_mov_b64 s[6:7], exec
	v_mbcnt_lo_u32_b32 v0, s6, 0
	v_mbcnt_hi_u32_b32 v0, s7, v0
	v_cmp_eq_u32_e32 vcc, 0, v0
	s_waitcnt vmcnt(0)
	s_and_saveexec_b64 s[8:9], vcc
	s_cbranch_execz .LBB0_495
	s_bcnt1_i32_b64 s2, s[6:7]
	v_mov_b32_e32 v0, 0x2000
	v_mov_b32_e32 v1, s2
.LBB0_495:
	s_or_b64 exec, exec, s[8:9]
	s_waitcnt vmcnt(0)

; __device__ __forceinline__ unsigned xb_ld(unsigned* p)              { return __hip_atomic_load(p, __ATOMIC_RELAXED, __HIP_MEMORY_SCOPE_AGENT); }
; __device__ __forceinline__ unsigned xb_add(unsigned* p, unsigned v) { return __hip_atomic_fetch_add(p, v, __ATOMIC_RELAXED, __HIP_MEMORY_SCOPE_AGENT); }
; #define XB_SPIN(cond, bar) do { unsigned _sp = 0; while (cond) { __builtin_amdgcn_s_sleep(1); \
;     if ((++_sp & 255u) == 0u) { if (xb_ld(&(bar)[XB_TMO])) break; if (_sp > XB_SPIN_CAP) { atomicAdd(&(bar)[XB_TMO], 1u); break; } } } } while (0)
; __device__ __forceinline__ void xcd_barrier(unsigned* bar, volatile LAS unsigned* st, bool tid0) {
;     ...
;             const unsigned og = xb_add(&bar[XB_TOP], 1u);
;             const unsigned tg = og / nx;
;             if (og + 1u == (tg + 1u) * nx) xb_add(&bar[XB_TOPGEN], 1u);
;             else XB_SPIN(xb_ld(&bar[XB_TOPGEN]) == tg, bar);
.LBB0_587:
	s_or_b64 exec, exec, s[14:15]
	v_cvt_f32_u32_e32 v3, v0
	s_waitcnt vmcnt(0)
	v_readfirstlane_b32 s2, v2
	s_add_u32 s14, s52, 0x3500
	s_addc_u32 s15, s53, 0
	v_rcp_iflag_f32_e32 v3, v3
	v_add_u32_e32 v1, s2, v1
	v_add_u32_e32 v4, 1, v1
	s_mov_b64 s[16:17], -1
	v_mul_f32_e32 v2, 0x4f7ffffe, v3
	v_cvt_u32_f32_e32 v2, v2
	v_sub_u32_e32 v3, 0, v0
	v_mul_lo_u32 v3, v3, v2
	v_mul_hi_u32 v3, v2, v3
	v_add_u32_e32 v2, v2, v3
	v_mul_hi_u32 v2, v1, v2
	v_mul_lo_u32 v3, v2, v0
	v_sub_u32_e32 v1, v1, v3
	v_add_u32_e32 v5, 1, v2
	v_cmp_ge_u32_e32 vcc, v1, v0
	v_sub_u32_e32 v3, v1, v0
	s_nop 0
	v_cndmask_b32_e32 v2, v2, v5, vcc
	v_cndmask_b32_e32 v1, v1, v3, vcc
	v_add_u32_e32 v3, 1, v2
	v_cmp_ge_u32_e32 vcc, v1, v0
	s_nop 1
	v_cndmask_b32_e32 v2, v2, v3, vcc
	v_mul_lo_u32 v1, v0, v2
	v_add_u32_e32 v0, v1, v0
	v_cmp_ne_u32_e32 vcc, v4, v0
	v_mov_b64_e32 v[0:1], s[14:15]
	s_cbranch_vccnz .Lxb_bcast_skip_5
	v_mov_b32_e32 v3, 0x2400
	v_mov_b32_e32 v4, 1
	global_atomic_add v3, v4, s[52:53]
	global_atomic_add v3, v4, s[52:53] offset:256
	global_atomic_add v3, v4, s[52:53] offset:512
	global_atomic_add v3, v4, s[52:53] offset:768
	global_atomic_add v3, v4, s[52:53] offset:1024
	global_atomic_add v3, v4, s[52:53] offset:1280
	global_atomic_add v3, v4, s[52:53] offset:1536
	global_atomic_add v3, v4, s[52:53] offset:1792
	global_atomic_add v3, v4, s[52:53] offset:2048
	global_atomic_add v3, v4, s[52:53] offset:2304
	global_atomic_add v3, v4, s[52:53] offset:2560
	global_atomic_add v3, v4, s[52:53] offset:2816
	global_atomic_add v3, v4, s[52:53] offset:3072
	global_atomic_add v3, v4, s[52:53] offset:3328
	global_atomic_add v3, v4, s[52:53] offset:3584
	global_atomic_add v3, v4, s[52:53] offset:3840
.Lxb_bcast_skip_5:
	s_and_saveexec_b64 s[12:13], vcc
	s_cbranch_execz .LBB0_599
	v_mov_b32_e32 v0, 0
	global_load_dword v1, v0, s[14:15] sc1
	s_mov_b64 s[20:21], 0
	s_waitcnt vmcnt(0)
	v_cmp_eq_u32_e32 vcc, v1, v2
	s_and_saveexec_b64 s[18:19], vcc
	s_cbranch_execz .LBB0_598
	s_add_u32 s16, s52, 0x200
	s_addc_u32 s17, s53, 0
	s_mov_b32 s2, 1
	s_branch .LBB0_591

; __device__ __forceinline__ unsigned xb_add(unsigned* p, unsigned v) { return __hip_atomic_fetch_add(p, v, __ATOMIC_RELAXED, __HIP_MEMORY_SCOPE_AGENT); }
; __device__ __forceinline__ void xcd_barrier(unsigned* bar, volatile LAS unsigned* st, bool tid0) {
;     ...
;             __builtin_amdgcn_fence(__ATOMIC_ACQUIRE, "agent");
;             xb_add(&bar[XB_XGEN(x)], 1u);
;             asm volatile("s_waitcnt vmcnt(0)" ::: "memory");
.LBB0_601:
	s_or_b64 exec, exec, s[12:13]
	s_mov_b64 s[12:13], exec
	v_mbcnt_lo_u32_b32 v0, s12, 0
	v_mbcnt_hi_u32_b32 v0, s13, v0
	v_cmp_eq_u32_e32 vcc, 0, v0
	s_waitcnt vmcnt(0)
	s_and_saveexec_b64 s[14:15], vcc
	s_cbranch_execz .LBB0_603
	s_bcnt1_i32_b64 s2, s[12:13]
	v_mov_b32_e32 v0, 0x2000
	v_mov_b32_e32 v1, s2
.LBB0_603:
	s_or_b64 exec, exec, s[14:15]
	s_waitcnt vmcnt(0)

; __device__ __forceinline__ unsigned xb_add(unsigned* p, unsigned v) { return __hip_atomic_fetch_add(p, v, __ATOMIC_RELAXED, __HIP_MEMORY_SCOPE_AGENT); }
; __device__ __forceinline__ void xcd_barrier(unsigned* bar, volatile LAS unsigned* st, bool tid0) {
;     ...
;             __builtin_amdgcn_fence(__ATOMIC_ACQUIRE, "agent");
;             xb_add(&bar[XB_XGEN(x)], 1u);
;             asm volatile("s_waitcnt vmcnt(0)" ::: "memory");
.LBB0_692:
	s_or_b64 exec, exec, s[12:13]
	s_mov_b64 s[12:13], exec
	v_mbcnt_lo_u32_b32 v0, s12, 0
	v_mbcnt_hi_u32_b32 v0, s13, v0
	v_cmp_eq_u32_e32 vcc, 0, v0
	s_waitcnt vmcnt(0)
	s_and_saveexec_b64 s[14:15], vcc
	s_cbranch_execz .LBB0_694
	s_bcnt1_i32_b64 s2, s[12:13]
	v_mov_b32_e32 v0, 0x2000
	v_mov_b32_e32 v1, s2
.LBB0_694:
	s_or_b64 exec, exec, s[14:15]
	s_waitcnt vmcnt(0)

; __device__ __forceinline__ unsigned xb_add(unsigned* p, unsigned v) { return __hip_atomic_fetch_add(p, v, __ATOMIC_RELAXED, __HIP_MEMORY_SCOPE_AGENT); }
; __device__ __forceinline__ void xcd_barrier(unsigned* bar, volatile LAS unsigned* st, bool tid0) {
;     ...
;             __builtin_amdgcn_fence(__ATOMIC_ACQUIRE, "agent");
;             xb_add(&bar[XB_XGEN(x)], 1u);
;             asm volatile("s_waitcnt vmcnt(0)" ::: "memory");
.LBB0_750:
	s_or_b64 exec, exec, s[12:13]
	s_mov_b64 s[12:13], exec
	v_mbcnt_lo_u32_b32 v0, s12, 0
	v_mbcnt_hi_u32_b32 v0, s13, v0
	v_cmp_eq_u32_e32 vcc, 0, v0
	s_waitcnt vmcnt(0)
	s_and_saveexec_b64 s[14:15], vcc
	s_cbranch_execz .LBB0_752
	s_bcnt1_i32_b64 s2, s[12:13]
	v_mov_b32_e32 v0, 0x2000
	v_mov_b32_e32 v1, s2
.LBB0_752:
	s_or_b64 exec, exec, s[14:15]
	s_waitcnt vmcnt(0)

; __device__ __forceinline__ unsigned xb_ld(unsigned* p)              { return __hip_atomic_load(p, __ATOMIC_RELAXED, __HIP_MEMORY_SCOPE_AGENT); }
; __device__ __forceinline__ unsigned xb_add(unsigned* p, unsigned v) { return __hip_atomic_fetch_add(p, v, __ATOMIC_RELAXED, __HIP_MEMORY_SCOPE_AGENT); }
; #define XB_SPIN(cond, bar) do { unsigned _sp = 0; while (cond) { __builtin_amdgcn_s_sleep(1); \
;     if ((++_sp & 255u) == 0u) { if (xb_ld(&(bar)[XB_TMO])) break; if (_sp > XB_SPIN_CAP) { atomicAdd(&(bar)[XB_TMO], 1u); break; } } } } while (0)
; __device__ __forceinline__ void xcd_barrier(unsigned* bar, volatile LAS unsigned* st, bool tid0) {
;     ...
;             const unsigned og = xb_add(&bar[XB_TOP], 1u);
;             const unsigned tg = og / nx;
;             if (og + 1u == (tg + 1u) * nx) xb_add(&bar[XB_TOPGEN], 1u);
;             else XB_SPIN(xb_ld(&bar[XB_TOPGEN]) == tg, bar);
.LBB0_805:
	s_or_b64 exec, exec, s[16:17]
	v_cvt_f32_u32_e32 v3, v0
	s_waitcnt vmcnt(0)
	v_readfirstlane_b32 s2, v2
	s_add_u32 s16, s52, 0x3500
	s_addc_u32 s17, s53, 0
	v_rcp_iflag_f32_e32 v3, v3
	v_add_u32_e32 v1, s2, v1
	v_add_u32_e32 v4, 1, v1
	s_mov_b64 s[18:19], -1
	v_mul_f32_e32 v2, 0x4f7ffffe, v3
	v_cvt_u32_f32_e32 v2, v2
	v_sub_u32_e32 v3, 0, v0
	v_mul_lo_u32 v3, v3, v2
	v_mul_hi_u32 v3, v2, v3
	v_add_u32_e32 v2, v2, v3
	v_mul_hi_u32 v2, v1, v2
	v_mul_lo_u32 v3, v2, v0
	v_sub_u32_e32 v1, v1, v3
	v_add_u32_e32 v5, 1, v2
	v_cmp_ge_u32_e32 vcc, v1, v0
	v_sub_u32_e32 v3, v1, v0
	s_nop 0
	v_cndmask_b32_e32 v2, v2, v5, vcc
	v_cndmask_b32_e32 v1, v1, v3, vcc
	v_add_u32_e32 v3, 1, v2
	v_cmp_ge_u32_e32 vcc, v1, v0
	s_nop 1
	v_cndmask_b32_e32 v2, v2, v3, vcc
	v_mul_lo_u32 v1, v0, v2
	v_add_u32_e32 v0, v1, v0
	v_cmp_ne_u32_e32 vcc, v4, v0
	v_mov_b64_e32 v[0:1], s[16:17]
	s_cbranch_vccnz .Lxb_bcast_skip_8
	v_mov_b32_e32 v3, 0x2400
	v_mov_b32_e32 v4, 1
	global_atomic_add v3, v4, s[52:53]
	global_atomic_add v3, v4, s[52:53] offset:256
	global_atomic_add v3, v4, s[52:53] offset:512
	global_atomic_add v3, v4, s[52:53] offset:768
	global_atomic_add v3, v4, s[52:53] offset:1024
	global_atomic_add v3, v4, s[52:53] offset:1280
	global_atomic_add v3, v4, s[52:53] offset:1536
	global_atomic_add v3, v4, s[52:53] offset:1792
	global_atomic_add v3, v4, s[52:53] offset:2048
	global_atomic_add v3, v4, s[52:53] offset:2304
	global_atomic_add v3, v4, s[52:53] offset:2560
	global_atomic_add v3, v4, s[52:53] offset:2816
	global_atomic_add v3, v4, s[52:53] offset:3072
	global_atomic_add v3, v4, s[52:53] offset:3328
	global_atomic_add v3, v4, s[52:53] offset:3584
	global_atomic_add v3, v4, s[52:53] offset:3840
.Lxb_bcast_skip_8:
	s_and_saveexec_b64 s[14:15], vcc
	s_cbranch_execz .LBB0_817
	v_mov_b32_e32 v0, 0
	global_load_dword v1, v0, s[16:17] sc1
	s_mov_b64 s[22:23], 0
	s_waitcnt vmcnt(0)
	v_cmp_eq_u32_e32 vcc, v1, v2
	s_and_saveexec_b64 s[20:21], vcc
	s_cbranch_execz .LBB0_816
	s_add_u32 s18, s52, 0x200
	s_addc_u32 s19, s53, 0
	s_mov_b32 s2, 1
	s_branch .LBB0_809

; __device__ __forceinline__ unsigned xb_add(unsigned* p, unsigned v) { return __hip_atomic_fetch_add(p, v, __ATOMIC_RELAXED, __HIP_MEMORY_SCOPE_AGENT); }
; __device__ __forceinline__ void xcd_barrier(unsigned* bar, volatile LAS unsigned* st, bool tid0) {
;     ...
;             __builtin_amdgcn_fence(__ATOMIC_ACQUIRE, "agent");
;             xb_add(&bar[XB_XGEN(x)], 1u);
;             asm volatile("s_waitcnt vmcnt(0)" ::: "memory");
.LBB0_819:
	s_or_b64 exec, exec, s[14:15]
	s_mov_b64 s[14:15], exec
	v_mbcnt_lo_u32_b32 v0, s14, 0
	v_mbcnt_hi_u32_b32 v0, s15, v0
	v_cmp_eq_u32_e32 vcc, 0, v0
	s_waitcnt vmcnt(0)
	s_and_saveexec_b64 s[16:17], vcc
	s_cbranch_execz .LBB0_821
	s_bcnt1_i32_b64 s2, s[14:15]
	v_mov_b32_e32 v0, 0x2000
	v_mov_b32_e32 v1, s2
.LBB0_821:
	s_or_b64 exec, exec, s[16:17]
	s_waitcnt vmcnt(0)

; __device__ __forceinline__ unsigned xb_add(unsigned* p, unsigned v) { return __hip_atomic_fetch_add(p, v, __ATOMIC_RELAXED, __HIP_MEMORY_SCOPE_AGENT); }
; __device__ __forceinline__ void xcd_barrier(unsigned* bar, volatile LAS unsigned* st, bool tid0) {
;     ...
;             __builtin_amdgcn_fence(__ATOMIC_ACQUIRE, "agent");
;             xb_add(&bar[XB_XGEN(x)], 1u);
;             asm volatile("s_waitcnt vmcnt(0)" ::: "memory");
.LBB0_914:
	s_or_b64 exec, exec, s[14:15]
	s_mov_b64 s[14:15], exec
	v_mbcnt_lo_u32_b32 v0, s14, 0
	v_mbcnt_hi_u32_b32 v0, s15, v0
	v_cmp_eq_u32_e32 vcc, 0, v0
	s_waitcnt vmcnt(0)
	s_and_saveexec_b64 s[16:17], vcc
	s_cbranch_execz .LBB0_916
	s_bcnt1_i32_b64 s2, s[14:15]
	v_mov_b32_e32 v0, 0x2000
	v_mov_b32_e32 v1, s2
.LBB0_916:
	s_or_b64 exec, exec, s[16:17]
	s_waitcnt vmcnt(0)

; __device__ __forceinline__ unsigned xb_add(unsigned* p, unsigned v) { return __hip_atomic_fetch_add(p, v, __ATOMIC_RELAXED, __HIP_MEMORY_SCOPE_AGENT); }
; __device__ __forceinline__ void xcd_barrier(unsigned* bar, volatile LAS unsigned* st, bool tid0) {
;     ...
;             __builtin_amdgcn_fence(__ATOMIC_ACQUIRE, "agent");
;             xb_add(&bar[XB_XGEN(x)], 1u);
;             asm volatile("s_waitcnt vmcnt(0)" ::: "memory");
.LBB0_972:
	s_or_b64 exec, exec, s[14:15]
	s_mov_b64 s[14:15], exec
	v_mbcnt_lo_u32_b32 v0, s14, 0
	v_mbcnt_hi_u32_b32 v0, s15, v0
	v_cmp_eq_u32_e32 vcc, 0, v0
	s_waitcnt vmcnt(0)
	s_and_saveexec_b64 s[16:17], vcc
	s_cbranch_execz .LBB0_974
	s_bcnt1_i32_b64 s2, s[14:15]
	v_mov_b32_e32 v0, 0x2000
	v_mov_b32_e32 v1, s2
.LBB0_974:
	s_or_b64 exec, exec, s[16:17]
	s_waitcnt vmcnt(0)

; __device__ __forceinline__ unsigned xb_ld(unsigned* p)              { return __hip_atomic_load(p, __ATOMIC_RELAXED, __HIP_MEMORY_SCOPE_AGENT); }
; __device__ __forceinline__ unsigned xb_add(unsigned* p, unsigned v) { return __hip_atomic_fetch_add(p, v, __ATOMIC_RELAXED, __HIP_MEMORY_SCOPE_AGENT); }
; #define XB_SPIN(cond, bar) do { unsigned _sp = 0; while (cond) { __builtin_amdgcn_s_sleep(1); \
;     if ((++_sp & 255u) == 0u) { if (xb_ld(&(bar)[XB_TMO])) break; if (_sp > XB_SPIN_CAP) { atomicAdd(&(bar)[XB_TMO], 1u); break; } } } } while (0)
; __device__ __forceinline__ void xcd_barrier(unsigned* bar, volatile LAS unsigned* st, bool tid0) {
;     ...
;             const unsigned og = xb_add(&bar[XB_TOP], 1u);
;             const unsigned tg = og / nx;
;             if (og + 1u == (tg + 1u) * nx) xb_add(&bar[XB_TOPGEN], 1u);
;             else XB_SPIN(xb_ld(&bar[XB_TOPGEN]) == tg, bar);
.LBB0_1067:
	s_or_b64 exec, exec, s[8:9]
	v_cvt_f32_u32_e32 v3, v0
	s_waitcnt vmcnt(0)
	v_readfirstlane_b32 s6, v2
	s_add_u32 s8, s52, 0x3500
	s_addc_u32 s9, s53, 0
	v_rcp_iflag_f32_e32 v3, v3
	v_add_u32_e32 v1, s6, v1
	v_add_u32_e32 v4, 1, v1
	s_mov_b64 s[12:13], -1
	v_mul_f32_e32 v2, 0x4f7ffffe, v3
	v_cvt_u32_f32_e32 v2, v2
	v_sub_u32_e32 v3, 0, v0
	v_mul_lo_u32 v3, v3, v2
	v_mul_hi_u32 v3, v2, v3
	v_add_u32_e32 v2, v2, v3
	v_mul_hi_u32 v2, v1, v2
	v_mul_lo_u32 v3, v2, v0
	v_sub_u32_e32 v1, v1, v3
	v_add_u32_e32 v5, 1, v2
	v_cmp_ge_u32_e32 vcc, v1, v0
	v_sub_u32_e32 v3, v1, v0
	s_nop 0
	v_cndmask_b32_e32 v2, v2, v5, vcc
	v_cndmask_b32_e32 v1, v1, v3, vcc
	v_add_u32_e32 v3, 1, v2
	v_cmp_ge_u32_e32 vcc, v1, v0
	s_nop 1
	v_cndmask_b32_e32 v2, v2, v3, vcc
	v_mul_lo_u32 v1, v0, v2
	v_add_u32_e32 v0, v1, v0
	v_cmp_ne_u32_e32 vcc, v4, v0
	v_mov_b64_e32 v[0:1], s[8:9]
	s_cbranch_vccnz .Lxb_bcast_skip_11
	v_mov_b32_e32 v3, 0x2400
	v_mov_b32_e32 v4, 1
	global_atomic_add v3, v4, s[52:53]
	global_atomic_add v3, v4, s[52:53] offset:256
	global_atomic_add v3, v4, s[52:53] offset:512
	global_atomic_add v3, v4, s[52:53] offset:768
	global_atomic_add v3, v4, s[52:53] offset:1024
	global_atomic_add v3, v4, s[52:53] offset:1280
	global_atomic_add v3, v4, s[52:53] offset:1536
	global_atomic_add v3, v4, s[52:53] offset:1792
	global_atomic_add v3, v4, s[52:53] offset:2048
	global_atomic_add v3, v4, s[52:53] offset:2304
	global_atomic_add v3, v4, s[52:53] offset:2560
	global_atomic_add v3, v4, s[52:53] offset:2816
	global_atomic_add v3, v4, s[52:53] offset:3072
	global_atomic_add v3, v4, s[52:53] offset:3328
	global_atomic_add v3, v4, s[52:53] offset:3584
	global_atomic_add v3, v4, s[52:53] offset:3840
.Lxb_bcast_skip_11:
	s_and_saveexec_b64 s[6:7], vcc
	s_cbranch_execz .LBB0_1079
	v_mov_b32_e32 v0, 0
	global_load_dword v1, v0, s[8:9] sc1
	s_mov_b64 s[16:17], 0
	s_waitcnt vmcnt(0)
	v_cmp_eq_u32_e32 vcc, v1, v2
	s_and_saveexec_b64 s[14:15], vcc
	s_cbranch_execz .LBB0_1078
	s_add_u32 s12, s52, 0x200
	s_addc_u32 s13, s53, 0
	s_mov_b32 s26, 1
	s_branch .LBB0_1071

; __device__ __forceinline__ unsigned xb_add(unsigned* p, unsigned v) { return __hip_atomic_fetch_add(p, v, __ATOMIC_RELAXED, __HIP_MEMORY_SCOPE_AGENT); }
; __device__ __forceinline__ void xcd_barrier(unsigned* bar, volatile LAS unsigned* st, bool tid0) {
;     ...
;             __builtin_amdgcn_fence(__ATOMIC_ACQUIRE, "agent");
;             xb_add(&bar[XB_XGEN(x)], 1u);
;             asm volatile("s_waitcnt vmcnt(0)" ::: "memory");
.LBB0_1081:
	s_or_b64 exec, exec, s[6:7]
	s_mov_b64 s[6:7], exec
	v_mbcnt_lo_u32_b32 v0, s6, 0
	v_mbcnt_hi_u32_b32 v0, s7, v0
	v_cmp_eq_u32_e32 vcc, 0, v0
	s_waitcnt vmcnt(0)
	s_and_saveexec_b64 s[8:9], vcc
	s_cbranch_execz .LBB0_1083
	s_bcnt1_i32_b64 s6, s[6:7]
	v_mov_b32_e32 v0, 0x2000
	v_mov_b32_e32 v1, s6
.LBB0_1083:
	s_or_b64 exec, exec, s[8:9]
	s_waitcnt vmcnt(0)
